# v41 + K-loop headers aligned to 64 B
# speedup vs baseline: 1.0056x; 1.0056x over previous
.LBB0_158:
	s_ashr_i32 s15, s14, 31
	s_lshl_b64 s[16:17], s[14:15], 20
	s_add_u32 s16, s3, s16
	s_addc_u32 s17, s28, s17
	s_and_b64 s[18:19], s[4:5], exec
	s_cselect_b32 s15, s17, s23
	s_cselect_b32 s46, s16, s22
	s_ashr_i32 s13, s12, 31
	s_lshl_b64 s[18:19], s[12:13], 20
	s_add_u32 s18, s29, s18
	s_addc_u32 s19, s30, s19
	s_and_b64 s[26:27], s[4:5], exec
	s_cselect_b32 s13, s19, s25
	s_cselect_b32 s47, s18, s24
	s_add_u32 s22, s22, 0x80080
	s_addc_u32 s23, s23, 0
	s_add_u32 s48, s24, 0x100
	v_mov_b32_e32 v2, 0
	s_addc_u32 s49, s25, 0
	s_mov_b32 s50, -2
	v_mov_b32_e32 v3, v2
	v_mov_b32_e32 v4, v2
	v_mov_b32_e32 v5, v2
	v_mov_b32_e32 v10, v2
	v_mov_b32_e32 v11, v2
	v_mov_b32_e32 v12, v2
	v_mov_b32_e32 v13, v2
	v_mov_b32_e32 v18, v2
	v_mov_b32_e32 v19, v2
	v_mov_b32_e32 v20, v2
	v_mov_b32_e32 v21, v2
	v_mov_b32_e32 v26, v2
	v_mov_b32_e32 v27, v2
	v_mov_b32_e32 v28, v2
	v_mov_b32_e32 v29, v2
	v_mov_b32_e32 v34, v2
	v_mov_b32_e32 v35, v2
	v_mov_b32_e32 v36, v2
	v_mov_b32_e32 v37, v2
	v_mov_b32_e32 v42, v2
	v_mov_b32_e32 v43, v2
	v_mov_b32_e32 v44, v2
	v_mov_b32_e32 v45, v2
	v_mov_b32_e32 v50, v2
	v_mov_b32_e32 v51, v2
	v_mov_b32_e32 v52, v2
	v_mov_b32_e32 v53, v2
	v_mov_b32_e32 v58, v2
	v_mov_b32_e32 v59, v2
	v_mov_b32_e32 v60, v2
	v_mov_b32_e32 v61, v2
	v_mov_b32_e32 v6, v2
	v_mov_b32_e32 v7, v2
	v_mov_b32_e32 v8, v2
	v_mov_b32_e32 v9, v2
	v_mov_b32_e32 v14, v2
	v_mov_b32_e32 v15, v2
	v_mov_b32_e32 v16, v2
	v_mov_b32_e32 v17, v2
	v_mov_b32_e32 v22, v2
	v_mov_b32_e32 v23, v2
	v_mov_b32_e32 v24, v2
	v_mov_b32_e32 v25, v2
	v_mov_b32_e32 v30, v2
	v_mov_b32_e32 v31, v2
	v_mov_b32_e32 v32, v2
	v_mov_b32_e32 v33, v2
	v_mov_b32_e32 v38, v2
	v_mov_b32_e32 v39, v2
	v_mov_b32_e32 v40, v2
	v_mov_b32_e32 v41, v2
	v_mov_b32_e32 v46, v2
	v_mov_b32_e32 v47, v2
	v_mov_b32_e32 v48, v2
	v_mov_b32_e32 v49, v2
	v_mov_b32_e32 v54, v2
	v_mov_b32_e32 v55, v2
	v_mov_b32_e32 v56, v2
	v_mov_b32_e32 v57, v2
	v_mov_b32_e32 v62, v2
	v_mov_b32_e32 v63, v2
	v_mov_b32_e32 v64, v2
	v_mov_b32_e32 v65, v2
	v_mov_b32_e32 v66, v2
	v_mov_b32_e32 v67, v2
	v_mov_b32_e32 v68, v2
	v_mov_b32_e32 v69, v2
	v_mov_b32_e32 v74, v2
	v_mov_b32_e32 v75, v2
	v_mov_b32_e32 v76, v2
	v_mov_b32_e32 v77, v2
	v_mov_b32_e32 v82, v2
	v_mov_b32_e32 v83, v2
	v_mov_b32_e32 v84, v2
	v_mov_b32_e32 v85, v2
	v_mov_b32_e32 v90, v2
	v_mov_b32_e32 v91, v2
	v_mov_b32_e32 v92, v2
	v_mov_b32_e32 v93, v2
	v_mov_b32_e32 v98, v2
	v_mov_b32_e32 v99, v2
	v_mov_b32_e32 v100, v2
	v_mov_b32_e32 v101, v2
	v_mov_b32_e32 v106, v2
	v_mov_b32_e32 v107, v2
	v_mov_b32_e32 v108, v2
	v_mov_b32_e32 v109, v2
	v_mov_b32_e32 v114, v2
	v_mov_b32_e32 v115, v2
	v_mov_b32_e32 v116, v2
	v_mov_b32_e32 v117, v2
	v_mov_b32_e32 v122, v2
	v_mov_b32_e32 v123, v2
	v_mov_b32_e32 v124, v2
	v_mov_b32_e32 v125, v2
	v_mov_b32_e32 v70, v2
	v_mov_b32_e32 v71, v2
	v_mov_b32_e32 v72, v2
	v_mov_b32_e32 v73, v2
	v_mov_b32_e32 v78, v2
	v_mov_b32_e32 v79, v2
	v_mov_b32_e32 v80, v2
	v_mov_b32_e32 v81, v2
	v_mov_b32_e32 v86, v2
	v_mov_b32_e32 v87, v2
	v_mov_b32_e32 v88, v2
	v_mov_b32_e32 v89, v2
	v_mov_b32_e32 v94, v2
	v_mov_b32_e32 v95, v2
	v_mov_b32_e32 v96, v2
	v_mov_b32_e32 v97, v2
	v_mov_b32_e32 v102, v2
	v_mov_b32_e32 v103, v2
	v_mov_b32_e32 v104, v2
	v_mov_b32_e32 v105, v2
	v_mov_b32_e32 v110, v2
	v_mov_b32_e32 v111, v2
	v_mov_b32_e32 v112, v2
	v_mov_b32_e32 v113, v2
	v_mov_b32_e32 v118, v2
	v_mov_b32_e32 v119, v2
	v_mov_b32_e32 v120, v2
	v_mov_b32_e32 v121, v2
	v_mov_b32_e32 v126, v2
	v_mov_b32_e32 v127, v2
	v_mov_b32_e32 v128, v2
	v_mov_b32_e32 v129, v2
	.p2align 6

.LBB0_242:
	s_add_u32 s49, s22, 0x100
	v_mov_b32_e32 v2, 0
	s_addc_u32 s50, s23, 0
	s_mov_b32 s51, -2
	v_mov_b32_e32 v3, v2
	v_mov_b32_e32 v4, v2
	v_mov_b32_e32 v5, v2
	v_mov_b32_e32 v6, v2
	v_mov_b32_e32 v7, v2
	v_mov_b32_e32 v8, v2
	v_mov_b32_e32 v9, v2
	v_mov_b32_e32 v18, v2
	v_mov_b32_e32 v19, v2
	v_mov_b32_e32 v20, v2
	v_mov_b32_e32 v21, v2
	v_mov_b32_e32 v22, v2
	v_mov_b32_e32 v23, v2
	v_mov_b32_e32 v24, v2
	v_mov_b32_e32 v25, v2
	v_mov_b32_e32 v34, v2
	v_mov_b32_e32 v35, v2
	v_mov_b32_e32 v36, v2
	v_mov_b32_e32 v37, v2
	v_mov_b32_e32 v38, v2
	v_mov_b32_e32 v39, v2
	v_mov_b32_e32 v40, v2
	v_mov_b32_e32 v41, v2
	v_mov_b32_e32 v50, v2
	v_mov_b32_e32 v51, v2
	v_mov_b32_e32 v52, v2
	v_mov_b32_e32 v53, v2
	v_mov_b32_e32 v54, v2
	v_mov_b32_e32 v55, v2
	v_mov_b32_e32 v56, v2
	v_mov_b32_e32 v57, v2
	v_mov_b32_e32 v10, v2
	v_mov_b32_e32 v11, v2
	v_mov_b32_e32 v12, v2
	v_mov_b32_e32 v13, v2
	v_mov_b32_e32 v14, v2
	v_mov_b32_e32 v15, v2
	v_mov_b32_e32 v16, v2
	v_mov_b32_e32 v17, v2
	v_mov_b32_e32 v26, v2
	v_mov_b32_e32 v27, v2
	v_mov_b32_e32 v28, v2
	v_mov_b32_e32 v29, v2
	v_mov_b32_e32 v30, v2
	v_mov_b32_e32 v31, v2
	v_mov_b32_e32 v32, v2
	v_mov_b32_e32 v33, v2
	v_mov_b32_e32 v42, v2
	v_mov_b32_e32 v43, v2
	v_mov_b32_e32 v44, v2
	v_mov_b32_e32 v45, v2
	v_mov_b32_e32 v46, v2
	v_mov_b32_e32 v47, v2
	v_mov_b32_e32 v48, v2
	v_mov_b32_e32 v49, v2
	v_mov_b32_e32 v58, v2
	v_mov_b32_e32 v59, v2
	v_mov_b32_e32 v60, v2
	v_mov_b32_e32 v61, v2
	v_mov_b32_e32 v62, v2
	v_mov_b32_e32 v63, v2
	v_mov_b32_e32 v64, v2
	v_mov_b32_e32 v65, v2
	v_mov_b32_e32 v66, v2
	v_mov_b32_e32 v67, v2
	v_mov_b32_e32 v68, v2
	v_mov_b32_e32 v69, v2
	v_mov_b32_e32 v70, v2
	v_mov_b32_e32 v71, v2
	v_mov_b32_e32 v72, v2
	v_mov_b32_e32 v73, v2
	v_mov_b32_e32 v82, v2
	v_mov_b32_e32 v83, v2
	v_mov_b32_e32 v84, v2
	v_mov_b32_e32 v85, v2
	v_mov_b32_e32 v86, v2
	v_mov_b32_e32 v87, v2
	v_mov_b32_e32 v88, v2
	v_mov_b32_e32 v89, v2
	v_mov_b32_e32 v106, v2
	v_mov_b32_e32 v107, v2
	v_mov_b32_e32 v108, v2
	v_mov_b32_e32 v109, v2
	v_mov_b32_e32 v110, v2
	v_mov_b32_e32 v111, v2
	v_mov_b32_e32 v112, v2
	v_mov_b32_e32 v113, v2
	v_mov_b32_e32 v130, v2
	v_mov_b32_e32 v131, v2
	v_mov_b32_e32 v132, v2
	v_mov_b32_e32 v133, v2
	v_mov_b32_e32 v134, v2
	v_mov_b32_e32 v135, v2
	v_mov_b32_e32 v136, v2
	v_mov_b32_e32 v137, v2
	v_mov_b32_e32 v74, v2
	v_mov_b32_e32 v75, v2
	v_mov_b32_e32 v76, v2
	v_mov_b32_e32 v77, v2
	v_mov_b32_e32 v78, v2
	v_mov_b32_e32 v79, v2
	v_mov_b32_e32 v80, v2
	v_mov_b32_e32 v81, v2
	v_mov_b32_e32 v94, v2
	v_mov_b32_e32 v95, v2
	v_mov_b32_e32 v96, v2
	v_mov_b32_e32 v97, v2
	v_mov_b32_e32 v98, v2
	v_mov_b32_e32 v99, v2
	v_mov_b32_e32 v100, v2
	v_mov_b32_e32 v101, v2
	v_mov_b32_e32 v118, v2
	v_mov_b32_e32 v119, v2
	v_mov_b32_e32 v120, v2
	v_mov_b32_e32 v121, v2
	v_mov_b32_e32 v122, v2
	v_mov_b32_e32 v123, v2
	v_mov_b32_e32 v124, v2
	v_mov_b32_e32 v125, v2
	v_mov_b32_e32 v146, v2
	v_mov_b32_e32 v147, v2
	v_mov_b32_e32 v148, v2
	v_mov_b32_e32 v149, v2
	v_mov_b32_e32 v150, v2
	v_mov_b32_e32 v151, v2
	v_mov_b32_e32 v152, v2
	v_mov_b32_e32 v153, v2
	.p2align 6

.LBB0_442:
	s_ashr_i32 s19, s18, 31
	s_lshl_b64 s[20:21], s[18:19], 20
	s_add_u32 s20, s35, s20
	s_addc_u32 s21, s36, s21
	s_and_b64 s[22:23], s[4:5], exec
	s_cselect_b32 s19, s21, s27
	s_cselect_b32 s51, s20, s26
	s_ashr_i32 s17, s16, 31
	s_lshl_b64 s[22:23], s[16:17], 20
	s_add_u32 s22, s37, s22
	s_addc_u32 s23, s38, s23
	s_and_b64 s[30:31], s[4:5], exec
	s_cselect_b32 s17, s23, s29
	s_cselect_b32 s52, s22, s28
	s_add_u32 s26, s26, 0x80080
	s_addc_u32 s27, s27, 0
	s_add_u32 s53, s28, 0x100
	v_mov_b32_e32 v2, 0
	s_addc_u32 s54, s29, 0
	s_mov_b32 s55, -2
	v_mov_b32_e32 v3, v2
	v_mov_b32_e32 v4, v2
	v_mov_b32_e32 v5, v2
	v_mov_b32_e32 v6, v2
	v_mov_b32_e32 v7, v2
	v_mov_b32_e32 v8, v2
	v_mov_b32_e32 v9, v2
	v_mov_b32_e32 v14, v2
	v_mov_b32_e32 v15, v2
	v_mov_b32_e32 v16, v2
	v_mov_b32_e32 v17, v2
	v_mov_b32_e32 v22, v2
	v_mov_b32_e32 v23, v2
	v_mov_b32_e32 v24, v2
	v_mov_b32_e32 v25, v2
	v_mov_b32_e32 v30, v2
	v_mov_b32_e32 v31, v2
	v_mov_b32_e32 v32, v2
	v_mov_b32_e32 v33, v2
	v_mov_b32_e32 v38, v2
	v_mov_b32_e32 v39, v2
	v_mov_b32_e32 v40, v2
	v_mov_b32_e32 v41, v2
	v_mov_b32_e32 v46, v2
	v_mov_b32_e32 v47, v2
	v_mov_b32_e32 v48, v2
	v_mov_b32_e32 v49, v2
	v_mov_b32_e32 v54, v2
	v_mov_b32_e32 v55, v2
	v_mov_b32_e32 v56, v2
	v_mov_b32_e32 v57, v2
	v_mov_b32_e32 v10, v2
	v_mov_b32_e32 v11, v2
	v_mov_b32_e32 v12, v2
	v_mov_b32_e32 v13, v2
	v_mov_b32_e32 v18, v2
	v_mov_b32_e32 v19, v2
	v_mov_b32_e32 v20, v2
	v_mov_b32_e32 v21, v2
	v_mov_b32_e32 v26, v2
	v_mov_b32_e32 v27, v2
	v_mov_b32_e32 v28, v2
	v_mov_b32_e32 v29, v2
	v_mov_b32_e32 v34, v2
	v_mov_b32_e32 v35, v2
	v_mov_b32_e32 v36, v2
	v_mov_b32_e32 v37, v2
	v_mov_b32_e32 v42, v2
	v_mov_b32_e32 v43, v2
	v_mov_b32_e32 v44, v2
	v_mov_b32_e32 v45, v2
	v_mov_b32_e32 v50, v2
	v_mov_b32_e32 v51, v2
	v_mov_b32_e32 v52, v2
	v_mov_b32_e32 v53, v2
	v_mov_b32_e32 v58, v2
	v_mov_b32_e32 v59, v2
	v_mov_b32_e32 v60, v2
	v_mov_b32_e32 v61, v2
	v_mov_b32_e32 v62, v2
	v_mov_b32_e32 v63, v2
	v_mov_b32_e32 v64, v2
	v_mov_b32_e32 v65, v2
	v_mov_b32_e32 v66, v2
	v_mov_b32_e32 v67, v2
	v_mov_b32_e32 v68, v2
	v_mov_b32_e32 v69, v2
	v_mov_b32_e32 v70, v2
	v_mov_b32_e32 v71, v2
	v_mov_b32_e32 v72, v2
	v_mov_b32_e32 v73, v2
	v_mov_b32_e32 v78, v2
	v_mov_b32_e32 v79, v2
	v_mov_b32_e32 v80, v2
	v_mov_b32_e32 v81, v2
	v_mov_b32_e32 v86, v2
	v_mov_b32_e32 v87, v2
	v_mov_b32_e32 v88, v2
	v_mov_b32_e32 v89, v2
	v_mov_b32_e32 v94, v2
	v_mov_b32_e32 v95, v2
	v_mov_b32_e32 v96, v2
	v_mov_b32_e32 v97, v2
	v_mov_b32_e32 v102, v2
	v_mov_b32_e32 v103, v2
	v_mov_b32_e32 v104, v2
	v_mov_b32_e32 v105, v2
	v_mov_b32_e32 v110, v2
	v_mov_b32_e32 v111, v2
	v_mov_b32_e32 v112, v2
	v_mov_b32_e32 v113, v2
	v_mov_b32_e32 v118, v2
	v_mov_b32_e32 v119, v2
	v_mov_b32_e32 v120, v2
	v_mov_b32_e32 v121, v2
	v_mov_b32_e32 v74, v2
	v_mov_b32_e32 v75, v2
	v_mov_b32_e32 v76, v2
	v_mov_b32_e32 v77, v2
	v_mov_b32_e32 v82, v2
	v_mov_b32_e32 v83, v2
	v_mov_b32_e32 v84, v2
	v_mov_b32_e32 v85, v2
	v_mov_b32_e32 v90, v2
	v_mov_b32_e32 v91, v2
	v_mov_b32_e32 v92, v2
	v_mov_b32_e32 v93, v2
	v_mov_b32_e32 v98, v2
	v_mov_b32_e32 v99, v2
	v_mov_b32_e32 v100, v2
	v_mov_b32_e32 v101, v2
	v_mov_b32_e32 v106, v2
	v_mov_b32_e32 v107, v2
	v_mov_b32_e32 v108, v2
	v_mov_b32_e32 v109, v2
	v_mov_b32_e32 v114, v2
	v_mov_b32_e32 v115, v2
	v_mov_b32_e32 v116, v2
	v_mov_b32_e32 v117, v2
	v_mov_b32_e32 v122, v2
	v_mov_b32_e32 v123, v2
	v_mov_b32_e32 v124, v2
	v_mov_b32_e32 v125, v2
	v_mov_b32_e32 v126, v2
	v_mov_b32_e32 v127, v2
	v_mov_b32_e32 v128, v2
	v_mov_b32_e32 v129, v2
	.p2align 6

.LBB0_1125:
	s_ashr_i32 s19, s18, 31
	s_lshl_b64 s[0:1], s[18:19], 20
	s_add_u32 s20, s3, s0
	s_addc_u32 s21, s36, s1
	s_and_b64 s[0:1], s[4:5], exec
	s_cselect_b32 s19, s21, s29
	s_cselect_b32 s25, s20, s28
	s_ashr_i32 s17, s16, 31
	s_lshl_b64 s[0:1], s[16:17], 20
	s_add_u32 s22, s37, s0
	s_addc_u32 s23, s38, s1
	s_and_b64 s[0:1], s[4:5], exec
	s_cselect_b32 s17, s23, s31
	s_cselect_b32 s27, s22, s30
	s_add_u32 s28, s28, 0x80080
	s_addc_u32 s29, s29, 0
	s_add_u32 s51, s30, 0x100
	v_mov_b32_e32 v2, 0
	s_addc_u32 s52, s31, 0
	s_mov_b32 s53, -2
	v_mov_b32_e32 v3, v2
	v_mov_b32_e32 v4, v2
	v_mov_b32_e32 v5, v2
	v_mov_b32_e32 v6, v2
	v_mov_b32_e32 v7, v2
	v_mov_b32_e32 v8, v2
	v_mov_b32_e32 v9, v2
	v_mov_b32_e32 v18, v2
	v_mov_b32_e32 v19, v2
	v_mov_b32_e32 v20, v2
	v_mov_b32_e32 v21, v2
	v_mov_b32_e32 v22, v2
	v_mov_b32_e32 v23, v2
	v_mov_b32_e32 v24, v2
	v_mov_b32_e32 v25, v2
	v_mov_b32_e32 v34, v2
	v_mov_b32_e32 v35, v2
	v_mov_b32_e32 v36, v2
	v_mov_b32_e32 v37, v2
	v_mov_b32_e32 v38, v2
	v_mov_b32_e32 v39, v2
	v_mov_b32_e32 v40, v2
	v_mov_b32_e32 v41, v2
	v_mov_b32_e32 v50, v2
	v_mov_b32_e32 v51, v2
	v_mov_b32_e32 v52, v2
	v_mov_b32_e32 v53, v2
	v_mov_b32_e32 v54, v2
	v_mov_b32_e32 v55, v2
	v_mov_b32_e32 v56, v2
	v_mov_b32_e32 v57, v2
	v_mov_b32_e32 v10, v2
	v_mov_b32_e32 v11, v2
	v_mov_b32_e32 v12, v2
	v_mov_b32_e32 v13, v2
	v_mov_b32_e32 v14, v2
	v_mov_b32_e32 v15, v2
	v_mov_b32_e32 v16, v2
	v_mov_b32_e32 v17, v2
	v_mov_b32_e32 v26, v2
	v_mov_b32_e32 v27, v2
	v_mov_b32_e32 v28, v2
	v_mov_b32_e32 v29, v2
	v_mov_b32_e32 v30, v2
	v_mov_b32_e32 v31, v2
	v_mov_b32_e32 v32, v2
	v_mov_b32_e32 v33, v2
	v_mov_b32_e32 v42, v2
	v_mov_b32_e32 v43, v2
	v_mov_b32_e32 v44, v2
	v_mov_b32_e32 v45, v2
	v_mov_b32_e32 v46, v2
	v_mov_b32_e32 v47, v2
	v_mov_b32_e32 v48, v2
	v_mov_b32_e32 v49, v2
	v_mov_b32_e32 v58, v2
	v_mov_b32_e32 v59, v2
	v_mov_b32_e32 v60, v2
	v_mov_b32_e32 v61, v2
	v_mov_b32_e32 v62, v2
	v_mov_b32_e32 v63, v2
	v_mov_b32_e32 v64, v2
	v_mov_b32_e32 v65, v2
	v_mov_b32_e32 v66, v2
	v_mov_b32_e32 v67, v2
	v_mov_b32_e32 v68, v2
	v_mov_b32_e32 v69, v2
	v_mov_b32_e32 v70, v2
	v_mov_b32_e32 v71, v2
	v_mov_b32_e32 v72, v2
	v_mov_b32_e32 v73, v2
	v_mov_b32_e32 v82, v2
	v_mov_b32_e32 v83, v2
	v_mov_b32_e32 v84, v2
	v_mov_b32_e32 v85, v2
	v_mov_b32_e32 v86, v2
	v_mov_b32_e32 v87, v2
	v_mov_b32_e32 v88, v2
	v_mov_b32_e32 v89, v2
	v_mov_b32_e32 v106, v2
	v_mov_b32_e32 v107, v2
	v_mov_b32_e32 v108, v2
	v_mov_b32_e32 v109, v2
	v_mov_b32_e32 v110, v2
	v_mov_b32_e32 v111, v2
	v_mov_b32_e32 v112, v2
	v_mov_b32_e32 v113, v2
	v_mov_b32_e32 v130, v2
	v_mov_b32_e32 v131, v2
	v_mov_b32_e32 v132, v2
	v_mov_b32_e32 v133, v2
	v_mov_b32_e32 v134, v2
	v_mov_b32_e32 v135, v2
	v_mov_b32_e32 v136, v2
	v_mov_b32_e32 v137, v2
	v_mov_b32_e32 v74, v2
	v_mov_b32_e32 v75, v2
	v_mov_b32_e32 v76, v2
	v_mov_b32_e32 v77, v2
	v_mov_b32_e32 v78, v2
	v_mov_b32_e32 v79, v2
	v_mov_b32_e32 v80, v2
	v_mov_b32_e32 v81, v2
	v_mov_b32_e32 v94, v2
	v_mov_b32_e32 v95, v2
	v_mov_b32_e32 v96, v2
	v_mov_b32_e32 v97, v2
	v_mov_b32_e32 v98, v2
	v_mov_b32_e32 v99, v2
	v_mov_b32_e32 v100, v2
	v_mov_b32_e32 v101, v2
	v_mov_b32_e32 v118, v2
	v_mov_b32_e32 v119, v2
	v_mov_b32_e32 v120, v2
	v_mov_b32_e32 v121, v2
	v_mov_b32_e32 v122, v2
	v_mov_b32_e32 v123, v2
	v_mov_b32_e32 v124, v2
	v_mov_b32_e32 v125, v2
	v_mov_b32_e32 v146, v2
	v_mov_b32_e32 v147, v2
	v_mov_b32_e32 v148, v2
	v_mov_b32_e32 v149, v2
	v_mov_b32_e32 v150, v2
	v_mov_b32_e32 v151, v2
	v_mov_b32_e32 v152, v2
	v_mov_b32_e32 v153, v2
	.p2align 6
